# conv phase rewritten: bias and tap weights hoisted out of the item loop, four x taps loaded together, two items in flight, no store-completion waits
# speedup vs baseline: 1.0206x; 1.0104x over previous
.LBB0_671:
	s_mov_b32 s0, s37
	s_lshl_b32 s36, s72, 11
	s_ashr_i32 s1, s0, 31
	v_readlane_b32 s2, v251, 6
	s_add_u32 s0, s2, s0
	v_readlane_b32 s2, v251, 7
	s_mov_b32 s48, s37
	s_addc_u32 s1, s2, s1
	s_ashr_i32 s49, s48, 31
	v_readlane_b32 s2, v251, 10
	s_add_u32 s18, s2, s48
	v_readlane_b32 s2, v251, 11
	s_addc_u32 s19, s2, s49
	s_mov_b32 s50, s37
	s_mov_b32 s52, s37
	s_mov_b32 s6, s37
	s_mov_b32 s8, s37
	v_readlane_b32 s2, v252, 43
	v_mbcnt_lo_u32_b32 v0, -1, 0
	v_mbcnt_hi_u32_b32 v0, -1, v0
	s_mov_b32 s93, s47
	s_waitcnt vmcnt(0)
	v_add_u32_e32 v18, s2, v0
	s_mov_b32 s2, 0x200000
	v_cmp_gt_i32_e32 vcc, s2, v18
	s_and_saveexec_b64 s[4:5], vcc
	v_readlane_b32 s44, v252, 44
	v_readlane_b32 s34, v252, 46
	v_readlane_b32 s46, v252, 48
	v_readlane_b32 s20, v252, 50
	v_readlane_b32 s24, v252, 52
	v_readlane_b32 s45, v252, 45
	v_readlane_b32 s35, v252, 47
	v_readlane_b32 s47, v252, 49
	v_readlane_b32 s21, v252, 51
	v_readlane_b32 s25, v252, 53
	v_readlane_b32 s14, v254, 60
	s_mov_b64 s[22:23], 0x2000
	s_mov_b64 s[26:27], 0x4000
	s_cbranch_execz .LBB0_680
	s_ashr_i32 s7, s6, 31
	s_lshl_b32 s2, s72, 13
	s_lshl_b64 s[6:7], s[6:7], 3
	s_add_u32 s6, s96, s6
	s_addc_u32 s7, s97, s7
	s_load_dwordx2 s[6:7], s[6:7], 0x18
	s_mov_b32 s3, s37
	s_lshl_b64 s[2:3], s[2:3], 2
	v_lshlrev_b32_e32 v19, 3, v18
	s_mov_b64 s[10:11], 0
	s_waitcnt lgkmcnt(0)
	s_add_u32 s6, s6, s2
	s_addc_u32 s7, s7, s3
	s_ashr_i32 s9, s8, 31
	s_lshl_b64 s[2:3], s[8:9], 3
	s_add_u32 s2, s96, s2
	s_addc_u32 s3, s97, s3
	s_load_dwordx2 s[2:3], s[2:3], 0x20
	s_lshl_b64 s[8:9], s[36:37], 2
	s_waitcnt lgkmcnt(0)
	s_add_u32 s8, s2, s8
	s_addc_u32 s9, s3, s9
	v_and_b32_e32 v10, 0x7f8, v19
	v_lshlrev_b32_e32 v0, 2, v10
	v_lshlrev_b32_e32 v14, 1, v10
	global_load_dwordx4 v[2:5], v0, s[8:9]
	global_load_dwordx4 v[6:9], v0, s[8:9] offset:16
	global_load_dwordx4 v[20:23], v0, s[6:7]
	global_load_dwordx4 v[24:27], v0, s[6:7] offset:16
	v_add_u32_e32 v11, 0x2000, v0
	global_load_dwordx4 v[28:31], v11, s[6:7]
	global_load_dwordx4 v[32:35], v11, s[6:7] offset:16
	v_add_u32_e32 v11, 0x4000, v0
	global_load_dwordx4 v[36:39], v11, s[6:7]
	global_load_dwordx4 v[40:43], v11, s[6:7] offset:16
	v_add_u32_e32 v11, 0x6000, v0
	global_load_dwordx4 v[44:47], v11, s[6:7]
	global_load_dwordx4 v[48:51], v11, s[6:7] offset:16
	v_readfirstlane_b32 s12, v18
	v_mov_b32_e32 v88, v18
	v_lshrrev_b32_e32 v89, 8, v88
	v_and_b32_e32 v85, 0x7ff, v89
	v_lshl_or_b32 v84, v89, 12, v14
	v_add_u32_e32 v90, -3, v89
	v_max_i32_e32 v90, 0, v90
	v_mad_u32_u24 v90, v90, s28, v14
	v_add_u32_e32 v91, -2, v89
	v_max_i32_e32 v91, 0, v91
	v_mad_u32_u24 v91, v91, s28, v14
	v_add_u32_e32 v92, -1, v89
	v_max_i32_e32 v92, 0, v92
	v_mad_u32_u24 v92, v92, s28, v14
	v_mad_u32_u24 v93, v89, s28, v14
	global_load_dwordx4 v[52:55], v90, s[18:19]
	global_load_dwordx4 v[56:59], v91, s[18:19]
	global_load_dwordx4 v[60:63], v92, s[18:19]
	global_load_dwordx4 v[64:67], v93, s[18:19]
	v_add_u32_e32 v88, s15, v88
	v_min_u32_e32 v88, 0x1fffff, v88
	v_lshrrev_b32_e32 v89, 8, v88
	v_and_b32_e32 v87, 0x7ff, v89
	v_lshl_or_b32 v86, v89, 12, v14
	v_add_u32_e32 v90, -3, v89
	v_max_i32_e32 v90, 0, v90
	v_mad_u32_u24 v90, v90, s28, v14
	v_add_u32_e32 v91, -2, v89
	v_max_i32_e32 v91, 0, v91
	v_mad_u32_u24 v91, v91, s28, v14
	v_add_u32_e32 v92, -1, v89
	v_max_i32_e32 v92, 0, v92
	v_mad_u32_u24 v92, v92, s28, v14
	v_mad_u32_u24 v93, v89, s28, v14
	global_load_dwordx4 v[68:71], v90, s[18:19]
	global_load_dwordx4 v[72:75], v91, s[18:19]
	global_load_dwordx4 v[76:79], v92, s[18:19]
	global_load_dwordx4 v[80:83], v93, s[18:19]
	s_waitcnt vmcnt(4)
	v_cmp_gt_u32_e64 s[6:7], 3, v85
	v_cmp_gt_u32_e64 s[8:9], 2, v85
	v_cmp_gt_u32_e64 s[10:11], 1, v85
	s_nop 1
	v_cndmask_b32_e64 v52, v52, 0, s[6:7]
	v_cndmask_b32_e64 v53, v53, 0, s[6:7]
	v_cndmask_b32_e64 v54, v54, 0, s[6:7]
	v_cndmask_b32_e64 v55, v55, 0, s[6:7]
	v_lshlrev_b32_e32 v102, 16, v52
	v_and_b32_e32 v103, 0xffff0000, v52
	v_fma_f32 v94, v102, v20, v2
	v_fma_f32 v95, v103, v21, v3
	v_lshlrev_b32_e32 v102, 16, v53
	v_and_b32_e32 v103, 0xffff0000, v53
	v_fma_f32 v96, v102, v22, v4
	v_fma_f32 v97, v103, v23, v5
	v_lshlrev_b32_e32 v102, 16, v54
	v_and_b32_e32 v103, 0xffff0000, v54
	v_fma_f32 v98, v102, v24, v6
	v_fma_f32 v99, v103, v25, v7
	v_lshlrev_b32_e32 v102, 16, v55
	v_and_b32_e32 v103, 0xffff0000, v55
	v_fma_f32 v100, v102, v26, v8
	v_fma_f32 v101, v103, v27, v9
	v_cndmask_b32_e64 v56, v56, 0, s[8:9]
	v_cndmask_b32_e64 v57, v57, 0, s[8:9]
	v_cndmask_b32_e64 v58, v58, 0, s[8:9]
	v_cndmask_b32_e64 v59, v59, 0, s[8:9]
	v_lshlrev_b32_e32 v102, 16, v56
	v_and_b32_e32 v103, 0xffff0000, v56
	v_fma_f32 v94, v102, v28, v94
	v_fma_f32 v95, v103, v29, v95
	v_lshlrev_b32_e32 v102, 16, v57
	v_and_b32_e32 v103, 0xffff0000, v57
	v_fma_f32 v96, v102, v30, v96
	v_fma_f32 v97, v103, v31, v97
	v_lshlrev_b32_e32 v102, 16, v58
	v_and_b32_e32 v103, 0xffff0000, v58
	v_fma_f32 v98, v102, v32, v98
	v_fma_f32 v99, v103, v33, v99
	v_lshlrev_b32_e32 v102, 16, v59
	v_and_b32_e32 v103, 0xffff0000, v59
	v_fma_f32 v100, v102, v34, v100
	v_fma_f32 v101, v103, v35, v101
	v_cndmask_b32_e64 v60, v60, 0, s[10:11]
	v_cndmask_b32_e64 v61, v61, 0, s[10:11]
	v_cndmask_b32_e64 v62, v62, 0, s[10:11]
	v_cndmask_b32_e64 v63, v63, 0, s[10:11]
	v_lshlrev_b32_e32 v102, 16, v60
	v_and_b32_e32 v103, 0xffff0000, v60
	v_fma_f32 v94, v102, v36, v94
	v_fma_f32 v95, v103, v37, v95
	v_lshlrev_b32_e32 v102, 16, v61
	v_and_b32_e32 v103, 0xffff0000, v61
	v_fma_f32 v96, v102, v38, v96
	v_fma_f32 v97, v103, v39, v97
	v_lshlrev_b32_e32 v102, 16, v62
	v_and_b32_e32 v103, 0xffff0000, v62
	v_fma_f32 v98, v102, v40, v98
	v_fma_f32 v99, v103, v41, v99
	v_lshlrev_b32_e32 v102, 16, v63
	v_and_b32_e32 v103, 0xffff0000, v63
	v_fma_f32 v100, v102, v42, v100
	v_fma_f32 v101, v103, v43, v101
	v_lshlrev_b32_e32 v102, 16, v64
	v_and_b32_e32 v103, 0xffff0000, v64
	v_fma_f32 v94, v102, v44, v94
	v_fma_f32 v95, v103, v45, v95
	v_lshlrev_b32_e32 v102, 16, v65
	v_and_b32_e32 v103, 0xffff0000, v65
	v_fma_f32 v96, v102, v46, v96
	v_fma_f32 v97, v103, v47, v97
	v_lshlrev_b32_e32 v102, 16, v66
	v_and_b32_e32 v103, 0xffff0000, v66
	v_fma_f32 v98, v102, v48, v98
	v_fma_f32 v99, v103, v49, v99
	v_lshlrev_b32_e32 v102, 16, v67
	v_and_b32_e32 v103, 0xffff0000, v67
	v_fma_f32 v100, v102, v50, v100
	v_fma_f32 v101, v103, v51, v101
	v_cvt_pk_bf16_f32 v104, v94, v95
	v_cvt_pk_bf16_f32 v105, v96, v97
	v_cvt_pk_bf16_f32 v106, v98, v99
	v_cvt_pk_bf16_f32 v107, v100, v101
	global_store_dwordx4 v84, v[104:107], s[0:1]
	v_add_u32_e32 v88, s15, v88
	v_min_u32_e32 v88, 0x1fffff, v88
	v_lshrrev_b32_e32 v89, 8, v88
	v_and_b32_e32 v85, 0x7ff, v89
	v_lshl_or_b32 v84, v89, 12, v14
	v_add_u32_e32 v90, -3, v89
	v_max_i32_e32 v90, 0, v90
	v_mad_u32_u24 v90, v90, s28, v14
	v_add_u32_e32 v91, -2, v89
	v_max_i32_e32 v91, 0, v91
	v_mad_u32_u24 v91, v91, s28, v14
	v_add_u32_e32 v92, -1, v89
	v_max_i32_e32 v92, 0, v92
	v_mad_u32_u24 v92, v92, s28, v14
	v_mad_u32_u24 v93, v89, s28, v14
	global_load_dwordx4 v[52:55], v90, s[18:19]
	global_load_dwordx4 v[56:59], v91, s[18:19]
	global_load_dwordx4 v[60:63], v92, s[18:19]
	global_load_dwordx4 v[64:67], v93, s[18:19]
	s_add_u32 s12, s12, s15
.Lconv_loop:
	s_cmp_lt_u32 s12, 0x200000
	s_cbranch_scc0 .Lconv_done
	s_waitcnt vmcnt(5)
	v_cmp_gt_u32_e64 s[6:7], 3, v87
	v_cmp_gt_u32_e64 s[8:9], 2, v87
	v_cmp_gt_u32_e64 s[10:11], 1, v87
	s_nop 1
	v_cndmask_b32_e64 v68, v68, 0, s[6:7]
	v_cndmask_b32_e64 v69, v69, 0, s[6:7]
	v_cndmask_b32_e64 v70, v70, 0, s[6:7]
	v_cndmask_b32_e64 v71, v71, 0, s[6:7]
	v_lshlrev_b32_e32 v102, 16, v68
	v_and_b32_e32 v103, 0xffff0000, v68
	v_fma_f32 v94, v102, v20, v2
	v_fma_f32 v95, v103, v21, v3
	v_lshlrev_b32_e32 v102, 16, v69
	v_and_b32_e32 v103, 0xffff0000, v69
	v_fma_f32 v96, v102, v22, v4
	v_fma_f32 v97, v103, v23, v5
	v_lshlrev_b32_e32 v102, 16, v70
	v_and_b32_e32 v103, 0xffff0000, v70
	v_fma_f32 v98, v102, v24, v6
	v_fma_f32 v99, v103, v25, v7
	v_lshlrev_b32_e32 v102, 16, v71
	v_and_b32_e32 v103, 0xffff0000, v71
	v_fma_f32 v100, v102, v26, v8
	v_fma_f32 v101, v103, v27, v9
	v_cndmask_b32_e64 v72, v72, 0, s[8:9]
	v_cndmask_b32_e64 v73, v73, 0, s[8:9]
	v_cndmask_b32_e64 v74, v74, 0, s[8:9]
	v_cndmask_b32_e64 v75, v75, 0, s[8:9]
	v_lshlrev_b32_e32 v102, 16, v72
	v_and_b32_e32 v103, 0xffff0000, v72
	v_fma_f32 v94, v102, v28, v94
	v_fma_f32 v95, v103, v29, v95
	v_lshlrev_b32_e32 v102, 16, v73
	v_and_b32_e32 v103, 0xffff0000, v73
	v_fma_f32 v96, v102, v30, v96
	v_fma_f32 v97, v103, v31, v97
	v_lshlrev_b32_e32 v102, 16, v74
	v_and_b32_e32 v103, 0xffff0000, v74
	v_fma_f32 v98, v102, v32, v98
	v_fma_f32 v99, v103, v33, v99
	v_lshlrev_b32_e32 v102, 16, v75
	v_and_b32_e32 v103, 0xffff0000, v75
	v_fma_f32 v100, v102, v34, v100
	v_fma_f32 v101, v103, v35, v101
	v_cndmask_b32_e64 v76, v76, 0, s[10:11]
	v_cndmask_b32_e64 v77, v77, 0, s[10:11]
	v_cndmask_b32_e64 v78, v78, 0, s[10:11]
	v_cndmask_b32_e64 v79, v79, 0, s[10:11]
	v_lshlrev_b32_e32 v102, 16, v76
	v_and_b32_e32 v103, 0xffff0000, v76
	v_fma_f32 v94, v102, v36, v94
	v_fma_f32 v95, v103, v37, v95
	v_lshlrev_b32_e32 v102, 16, v77
	v_and_b32_e32 v103, 0xffff0000, v77
	v_fma_f32 v96, v102, v38, v96
	v_fma_f32 v97, v103, v39, v97
	v_lshlrev_b32_e32 v102, 16, v78
	v_and_b32_e32 v103, 0xffff0000, v78
	v_fma_f32 v98, v102, v40, v98
	v_fma_f32 v99, v103, v41, v99
	v_lshlrev_b32_e32 v102, 16, v79
	v_and_b32_e32 v103, 0xffff0000, v79
	v_fma_f32 v100, v102, v42, v100
	v_fma_f32 v101, v103, v43, v101
	v_lshlrev_b32_e32 v102, 16, v80
	v_and_b32_e32 v103, 0xffff0000, v80
	v_fma_f32 v94, v102, v44, v94
	v_fma_f32 v95, v103, v45, v95
	v_lshlrev_b32_e32 v102, 16, v81
	v_and_b32_e32 v103, 0xffff0000, v81
	v_fma_f32 v96, v102, v46, v96
	v_fma_f32 v97, v103, v47, v97
	v_lshlrev_b32_e32 v102, 16, v82
	v_and_b32_e32 v103, 0xffff0000, v82
	v_fma_f32 v98, v102, v48, v98
	v_fma_f32 v99, v103, v49, v99
	v_lshlrev_b32_e32 v102, 16, v83
	v_and_b32_e32 v103, 0xffff0000, v83
	v_fma_f32 v100, v102, v50, v100
	v_fma_f32 v101, v103, v51, v101
	v_cvt_pk_bf16_f32 v104, v94, v95
	v_cvt_pk_bf16_f32 v105, v96, v97
	v_cvt_pk_bf16_f32 v106, v98, v99
	v_cvt_pk_bf16_f32 v107, v100, v101
	global_store_dwordx4 v86, v[104:107], s[0:1]
	v_add_u32_e32 v88, s15, v88
	v_min_u32_e32 v88, 0x1fffff, v88
	v_lshrrev_b32_e32 v89, 8, v88
	v_and_b32_e32 v87, 0x7ff, v89
	v_lshl_or_b32 v86, v89, 12, v14
	v_add_u32_e32 v90, -3, v89
	v_max_i32_e32 v90, 0, v90
	v_mad_u32_u24 v90, v90, s28, v14
	v_add_u32_e32 v91, -2, v89
	v_max_i32_e32 v91, 0, v91
	v_mad_u32_u24 v91, v91, s28, v14
	v_add_u32_e32 v92, -1, v89
	v_max_i32_e32 v92, 0, v92
	v_mad_u32_u24 v92, v92, s28, v14
	v_mad_u32_u24 v93, v89, s28, v14
	global_load_dwordx4 v[68:71], v90, s[18:19]
	global_load_dwordx4 v[72:75], v91, s[18:19]
	global_load_dwordx4 v[76:79], v92, s[18:19]
	global_load_dwordx4 v[80:83], v93, s[18:19]
	s_add_u32 s12, s12, s15
	s_cmp_lt_u32 s12, 0x200000
	s_cbranch_scc0 .Lconv_done
	s_waitcnt vmcnt(5)
	v_cmp_gt_u32_e64 s[6:7], 3, v85
	v_cmp_gt_u32_e64 s[8:9], 2, v85
	v_cmp_gt_u32_e64 s[10:11], 1, v85
	s_nop 1
	v_cndmask_b32_e64 v52, v52, 0, s[6:7]
	v_cndmask_b32_e64 v53, v53, 0, s[6:7]
	v_cndmask_b32_e64 v54, v54, 0, s[6:7]
	v_cndmask_b32_e64 v55, v55, 0, s[6:7]
	v_lshlrev_b32_e32 v102, 16, v52
	v_and_b32_e32 v103, 0xffff0000, v52
	v_fma_f32 v94, v102, v20, v2
	v_fma_f32 v95, v103, v21, v3
	v_lshlrev_b32_e32 v102, 16, v53
	v_and_b32_e32 v103, 0xffff0000, v53
	v_fma_f32 v96, v102, v22, v4
	v_fma_f32 v97, v103, v23, v5
	v_lshlrev_b32_e32 v102, 16, v54
	v_and_b32_e32 v103, 0xffff0000, v54
	v_fma_f32 v98, v102, v24, v6
	v_fma_f32 v99, v103, v25, v7
	v_lshlrev_b32_e32 v102, 16, v55
	v_and_b32_e32 v103, 0xffff0000, v55
	v_fma_f32 v100, v102, v26, v8
	v_fma_f32 v101, v103, v27, v9
	v_cndmask_b32_e64 v56, v56, 0, s[8:9]
	v_cndmask_b32_e64 v57, v57, 0, s[8:9]
	v_cndmask_b32_e64 v58, v58, 0, s[8:9]
	v_cndmask_b32_e64 v59, v59, 0, s[8:9]
	v_lshlrev_b32_e32 v102, 16, v56
	v_and_b32_e32 v103, 0xffff0000, v56
	v_fma_f32 v94, v102, v28, v94
	v_fma_f32 v95, v103, v29, v95
	v_lshlrev_b32_e32 v102, 16, v57
	v_and_b32_e32 v103, 0xffff0000, v57
	v_fma_f32 v96, v102, v30, v96
	v_fma_f32 v97, v103, v31, v97
	v_lshlrev_b32_e32 v102, 16, v58
	v_and_b32_e32 v103, 0xffff0000, v58
	v_fma_f32 v98, v102, v32, v98
	v_fma_f32 v99, v103, v33, v99
	v_lshlrev_b32_e32 v102, 16, v59
	v_and_b32_e32 v103, 0xffff0000, v59
	v_fma_f32 v100, v102, v34, v100
	v_fma_f32 v101, v103, v35, v101
	v_cndmask_b32_e64 v60, v60, 0, s[10:11]
	v_cndmask_b32_e64 v61, v61, 0, s[10:11]
	v_cndmask_b32_e64 v62, v62, 0, s[10:11]
	v_cndmask_b32_e64 v63, v63, 0, s[10:11]
	v_lshlrev_b32_e32 v102, 16, v60
	v_and_b32_e32 v103, 0xffff0000, v60
	v_fma_f32 v94, v102, v36, v94
	v_fma_f32 v95, v103, v37, v95
	v_lshlrev_b32_e32 v102, 16, v61
	v_and_b32_e32 v103, 0xffff0000, v61
	v_fma_f32 v96, v102, v38, v96
	v_fma_f32 v97, v103, v39, v97
	v_lshlrev_b32_e32 v102, 16, v62
	v_and_b32_e32 v103, 0xffff0000, v62
	v_fma_f32 v98, v102, v40, v98
	v_fma_f32 v99, v103, v41, v99
	v_lshlrev_b32_e32 v102, 16, v63
	v_and_b32_e32 v103, 0xffff0000, v63
	v_fma_f32 v100, v102, v42, v100
	v_fma_f32 v101, v103, v43, v101
	v_lshlrev_b32_e32 v102, 16, v64
	v_and_b32_e32 v103, 0xffff0000, v64
	v_fma_f32 v94, v102, v44, v94
	v_fma_f32 v95, v103, v45, v95
	v_lshlrev_b32_e32 v102, 16, v65
	v_and_b32_e32 v103, 0xffff0000, v65
	v_fma_f32 v96, v102, v46, v96
	v_fma_f32 v97, v103, v47, v97
	v_lshlrev_b32_e32 v102, 16, v66
	v_and_b32_e32 v103, 0xffff0000, v66
	v_fma_f32 v98, v102, v48, v98
	v_fma_f32 v99, v103, v49, v99
	v_lshlrev_b32_e32 v102, 16, v67
	v_and_b32_e32 v103, 0xffff0000, v67
	v_fma_f32 v100, v102, v50, v100
	v_fma_f32 v101, v103, v51, v101
	v_cvt_pk_bf16_f32 v104, v94, v95
	v_cvt_pk_bf16_f32 v105, v96, v97
	v_cvt_pk_bf16_f32 v106, v98, v99
	v_cvt_pk_bf16_f32 v107, v100, v101
	global_store_dwordx4 v84, v[104:107], s[0:1]
	v_add_u32_e32 v88, s15, v88
	v_min_u32_e32 v88, 0x1fffff, v88
	v_lshrrev_b32_e32 v89, 8, v88
	v_and_b32_e32 v85, 0x7ff, v89
	v_lshl_or_b32 v84, v89, 12, v14
	v_add_u32_e32 v90, -3, v89
	v_max_i32_e32 v90, 0, v90
	v_mad_u32_u24 v90, v90, s28, v14
	v_add_u32_e32 v91, -2, v89
	v_max_i32_e32 v91, 0, v91
	v_mad_u32_u24 v91, v91, s28, v14
	v_add_u32_e32 v92, -1, v89
	v_max_i32_e32 v92, 0, v92
	v_mad_u32_u24 v92, v92, s28, v14
	v_mad_u32_u24 v93, v89, s28, v14
	global_load_dwordx4 v[52:55], v90, s[18:19]
	global_load_dwordx4 v[56:59], v91, s[18:19]
	global_load_dwordx4 v[60:63], v92, s[18:19]
	global_load_dwordx4 v[64:67], v93, s[18:19]
	s_add_u32 s12, s12, s15
	s_branch .Lconv_loop
.Lconv_done:
.LBB0_680:
	s_or_b64 exec, exec, s[4:5]
	s_waitcnt vmcnt(0)
	s_waitcnt vmcnt(0)
	s_barrier
	s_mov_b64 s[4:5], exec
	v_readlane_b32 s2, v251, 2
	v_readlane_b32 s3, v251, 3
	s_and_b64 s[2:3], s[4:5], s[2:3]
	s_mov_b64 exec, s[2:3]
	s_cbranch_execz .LBB0_728
	v_readlane_b32 s2, v255, 15
	s_waitcnt vmcnt(0) expcnt(0) lgkmcnt(0)
	s_nop 0
	v_mov_b32_e32 v0, s2
	ds_read_b32 v3, v0
	v_readlane_b32 s2, v255, 16
	s_waitcnt lgkmcnt(0)
	v_cmp_ne_u32_e32 vcc, 0, v3
	v_mov_b32_e32 v0, s2
	ds_read_b32 v2, v0
	s_cbranch_vccnz .LBB0_696
	s_mov_b32 s2, 1
	s_branch .LBB0_684
